# v30 + code placement A/B: one s_nop before the first GEMM loop head shifts all four GEMM loop bodies (and everything after) by 4 bytes, heads now at 0 mod 8
# baseline (speedup 1.0000x reference)
.LBB0_211:
	s_add_i32 s60, s60, 1
	s_mov_b64 s[36:37], s[18:19]
	s_mul_i32 s18, s60, s26
	s_add_i32 s38, s18, s2
	s_cmpk_gt_i32 s38, 0x1ff
	s_cselect_b64 s[44:45], -1, 0
	s_lshl_b32 s18, s38, 3
	s_and_b32 s18, s18, 56
	s_bfe_u32 s19, s38, 0x30003
	s_mov_b32 s27, s61
	s_or_b32 s61, s18, s19
	s_mov_b32 s3, s42
	s_ashr_i32 s42, s38, 6
	s_lshl_b32 s18, s61, 19
	s_mov_b64 s[4:5], s[20:21]
	s_add_u32 s20, s14, s18
	s_addc_u32 s21, s15, 0
	s_ashr_i32 s43, s42, 31
	s_lshl_b64 s[18:19], s[42:43], 19
	s_add_u32 s18, s16, s18
	s_addc_u32 s19, s17, s19
	s_cmpk_lt_i32 s38, 0x200
	s_cselect_b32 s38, s21, s5
	s_cselect_b32 s43, s20, s4
	s_cselect_b32 s62, s19, s37
	s_cselect_b32 s63, s18, s36
	s_add_u32 s64, s36, 0x100
	s_addc_u32 s65, s37, 0
	s_mov_b32 s66, -2
	s_waitcnt lgkmcnt(0)
	s_add_u32 s36, s4, 0x100
	s_addc_u32 s37, s5, 0
	s_add_i32 s67, 0, 0x10000
	v_add_u32_e32 v1, s67, v191
	ds_read_b128 v[34:37], v1
	ds_read_b128 v[38:41], v1 offset:1024
	ds_read_b128 v[42:45], v1 offset:2048
	ds_read_b128 v[46:49], v1 offset:3072
	s_cmp_eq_u32 s66, 12
	s_cselect_b32 s49, s38, s37
	s_cselect_b32 s48, s43, s36
	s_cselect_b32 s47, s62, s65
	s_cselect_b32 s46, s63, s64
	v_lshl_add_u64 v[186:187], s[4:5], 0, v[168:169]
	s_add_i32 m0, s53, 0xc000
	ds_read_b128 v[50:53], v206
	ds_read_b128 v[58:61], v206 offset:1024
	ds_read_b128 v[62:65], v206 offset:2048
	ds_read_b128 v[66:69], v206 offset:3072
	ds_read_b128 v[170:173], v206 offset:4096
	ds_read_b128 v[174:177], v206 offset:5120
	ds_read_b128 v[178:181], v206 offset:6144
	ds_read_b128 v[182:185], v206 offset:7168
	global_load_lds_dwordx4 v[186:187], off
	v_lshl_add_u64 v[186:187], s[4:5], 0, v[166:167]
	s_add_i32 m0, s53, 0xe000
	s_nop 0
	global_load_lds_dwordx4 v[186:187], off
	s_waitcnt lgkmcnt(8)
	s_barrier
	s_waitcnt lgkmcnt(0)
	s_waitcnt lgkmcnt(0)
	v_mfma_f32_16x16x32_bf16 v[158:161], v[34:37], v[50:53], 0
	v_mfma_f32_16x16x32_bf16 v[154:157], v[42:45], v[50:53], 0
	v_mfma_f32_16x16x32_bf16 v[142:145], v[34:37], v[62:65], 0
	v_mfma_f32_16x16x32_bf16 v[138:141], v[42:45], v[62:65], 0
	v_mfma_f32_16x16x32_bf16 v[126:129], v[34:37], v[170:173], 0
	v_mfma_f32_16x16x32_bf16 v[122:125], v[42:45], v[170:173], 0
	v_mfma_f32_16x16x32_bf16 v[110:113], v[34:37], v[178:181], 0
	v_mfma_f32_16x16x32_bf16 v[106:109], v[42:45], v[178:181], 0
	v_mfma_f32_16x16x32_bf16 v[158:161], v[38:41], v[58:61], v[158:161]
	v_mfma_f32_16x16x32_bf16 v[154:157], v[46:49], v[58:61], v[154:157]
	v_mfma_f32_16x16x32_bf16 v[142:145], v[38:41], v[66:69], v[142:145]
	v_mfma_f32_16x16x32_bf16 v[138:141], v[46:49], v[66:69], v[138:141]
	v_mfma_f32_16x16x32_bf16 v[126:129], v[38:41], v[174:177], v[126:129]
	v_mfma_f32_16x16x32_bf16 v[122:125], v[46:49], v[174:177], v[122:125]
	v_mfma_f32_16x16x32_bf16 v[110:113], v[38:41], v[182:185], v[110:113]
	v_mfma_f32_16x16x32_bf16 v[106:109], v[46:49], v[182:185], v[106:109]
	s_barrier
	v_mbcnt_lo_u32_b32 v250, -1, 0
	v_mbcnt_hi_u32_b32 v250, -1, v250
	v_lshlrev_b32_e32 v250, 4, v250
	s_lshl_b32 s32, s3, 10
	s_add_u32 s90, s8, s32
	s_addc_u32 s91, s9, 0
	s_add_u32 s92, s10, s32
	s_addc_u32 s93, s11, 0
	s_mov_b32 m0, 0x20840
	s_nop 0
	global_load_lds_dwordx4 v250, s[90:91]
	s_mov_b32 m0, 0x20c40
	s_nop 0
	global_load_lds_dwordx4 v250, s[92:93]
	s_add_i32 s68, 0, 0x14000
	s_add_i32 s4, s67, s52
	v_add_u32_e32 v1, s68, v191
	v_lshl_add_u64 v[214:215], s[46:47], 0, v[164:165]
	s_mov_b32 m0, s4
	ds_read_b128 v[186:189], v1
	ds_read_b128 v[208:211], v1 offset:1024
	ds_read_b128 v[222:225], v1 offset:2048
	ds_read_b128 v[226:229], v1 offset:3072
	global_load_lds_dwordx4 v[214:215], off
	v_lshl_add_u64 v[238:239], s[46:47], 0, v[162:163]
	s_add_i32 m0, s4, 0x2000
	s_nop 0
	global_load_lds_dwordx4 v[238:239], off
	s_barrier
	s_waitcnt lgkmcnt(0)
	s_waitcnt lgkmcnt(0)
	v_mfma_f32_16x16x32_bf16 v[150:153], v[186:189], v[50:53], 0
	v_mfma_f32_16x16x32_bf16 v[50:53], v[222:225], v[50:53], 0
	v_mfma_f32_16x16x32_bf16 v[150:153], v[208:211], v[58:61], v[150:153]
	v_mfma_f32_16x16x32_bf16 v[50:53], v[226:229], v[58:61], v[50:53]
	v_mfma_f32_16x16x32_bf16 v[58:61], v[186:189], v[62:65], 0
	v_mfma_f32_16x16x32_bf16 v[62:65], v[222:225], v[62:65], 0
	v_mfma_f32_16x16x32_bf16 v[114:117], v[222:225], v[170:173], 0
	v_mfma_f32_16x16x32_bf16 v[102:105], v[186:189], v[178:181], 0
	v_mfma_f32_16x16x32_bf16 v[98:101], v[222:225], v[178:181], 0
	v_mfma_f32_16x16x32_bf16 v[58:61], v[208:211], v[66:69], v[58:61]
	v_mfma_f32_16x16x32_bf16 v[62:65], v[226:229], v[66:69], v[62:65]
	v_mfma_f32_16x16x32_bf16 v[66:69], v[186:189], v[170:173], 0
	v_mfma_f32_16x16x32_bf16 v[114:117], v[226:229], v[174:177], v[114:117]
	v_mfma_f32_16x16x32_bf16 v[102:105], v[208:211], v[182:185], v[102:105]
	v_mfma_f32_16x16x32_bf16 v[98:101], v[226:229], v[182:185], v[98:101]
	v_mfma_f32_16x16x32_bf16 v[66:69], v[208:211], v[174:177], v[66:69]
	s_mov_b32 m0, s53
	v_lshl_add_u64 v[240:241], s[48:49], 0, v[164:165]
	s_barrier
	ds_read_b128 v[118:121], v206 offset:16384
	ds_read_b128 v[130:133], v206 offset:17408
	ds_read_b128 v[134:137], v206 offset:18432
	ds_read_b128 v[146:149], v206 offset:19456
	ds_read_b128 v[170:173], v206 offset:20480
	ds_read_b128 v[174:177], v206 offset:21504
	ds_read_b128 v[178:181], v206 offset:22528
	ds_read_b128 v[182:185], v206 offset:23552
	global_load_lds_dwordx4 v[240:241], off
	v_lshl_add_u64 v[242:243], s[48:49], 0, v[162:163]
	s_mov_b32 m0, s54
	s_nop 0
	global_load_lds_dwordx4 v[242:243], off
	s_barrier
	s_waitcnt lgkmcnt(0)
	s_waitcnt lgkmcnt(0)
	v_mfma_f32_16x16x32_bf16 v[94:97], v[34:37], v[118:121], 0
	v_mfma_f32_16x16x32_bf16 v[90:93], v[42:45], v[118:121], 0
	v_mfma_f32_16x16x32_bf16 v[78:81], v[34:37], v[134:137], 0
	v_mfma_f32_16x16x32_bf16 v[74:77], v[42:45], v[134:137], 0
	v_mfma_f32_16x16x32_bf16 v[30:33], v[34:37], v[170:173], 0
	v_mfma_f32_16x16x32_bf16 v[26:29], v[42:45], v[170:173], 0
	v_mfma_f32_16x16x32_bf16 v[14:17], v[34:37], v[178:181], 0
	v_mfma_f32_16x16x32_bf16 v[10:13], v[42:45], v[178:181], 0
	v_mfma_f32_16x16x32_bf16 v[94:97], v[38:41], v[130:133], v[94:97]
	v_mfma_f32_16x16x32_bf16 v[90:93], v[46:49], v[130:133], v[90:93]
	v_mfma_f32_16x16x32_bf16 v[78:81], v[38:41], v[146:149], v[78:81]
	v_mfma_f32_16x16x32_bf16 v[74:77], v[46:49], v[146:149], v[74:77]
	v_mfma_f32_16x16x32_bf16 v[30:33], v[38:41], v[174:177], v[30:33]
	v_mfma_f32_16x16x32_bf16 v[26:29], v[46:49], v[174:177], v[26:29]
	v_mfma_f32_16x16x32_bf16 v[14:17], v[38:41], v[182:185], v[14:17]
	v_mfma_f32_16x16x32_bf16 v[10:13], v[46:49], v[182:185], v[10:13]
	s_barrier
	s_add_u32 s4, s46, 0x40000
	s_addc_u32 s5, s47, 0
	s_add_i32 s67, s68, s52
	v_lshl_add_u64 v[34:35], s[4:5], 0, v[164:165]
	s_mov_b32 m0, s67
	s_nop 0
	global_load_lds_dwordx4 v[34:35], off
	v_lshl_add_u64 v[34:35], s[4:5], 0, v[162:163]
	s_add_i32 m0, s67, 0x2000
	s_nop 0
	global_load_lds_dwordx4 v[34:35], off
	s_waitcnt vmcnt(6)
	s_barrier
	v_mfma_f32_16x16x32_bf16 v[22:25], v[186:189], v[170:173], 0
	v_mfma_f32_16x16x32_bf16 v[18:21], v[222:225], v[170:173], 0
	v_mfma_f32_16x16x32_bf16 v[6:9], v[186:189], v[178:181], 0
	v_mfma_f32_16x16x32_bf16 v[2:5], v[222:225], v[178:181], 0
	v_mfma_f32_16x16x32_bf16 v[34:37], v[186:189], v[118:121], 0
	v_mfma_f32_16x16x32_bf16 v[38:41], v[222:225], v[118:121], 0
	v_mfma_f32_16x16x32_bf16 v[42:45], v[186:189], v[134:137], 0
	v_mfma_f32_16x16x32_bf16 v[46:49], v[222:225], v[134:137], 0
	v_mfma_f32_16x16x32_bf16 v[22:25], v[208:211], v[174:177], v[22:25]
	v_mfma_f32_16x16x32_bf16 v[18:21], v[226:229], v[174:177], v[18:21]
	v_mfma_f32_16x16x32_bf16 v[6:9], v[208:211], v[182:185], v[6:9]
	v_mfma_f32_16x16x32_bf16 v[2:5], v[226:229], v[182:185], v[2:5]
	v_mfma_f32_16x16x32_bf16 v[34:37], v[208:211], v[130:133], v[34:37]
	v_mfma_f32_16x16x32_bf16 v[38:41], v[226:229], v[130:133], v[38:41]
	v_mfma_f32_16x16x32_bf16 v[42:45], v[208:211], v[146:149], v[42:45]
	v_mfma_f32_16x16x32_bf16 v[46:49], v[226:229], v[146:149], v[46:49]
	s_add_i32 s67, 0, 0x18000
	v_add_u32_e32 v1, s67, v191
	s_barrier
	ds_read_b128 v[54:57], v1
	ds_read_b128 v[70:73], v1 offset:1024
	ds_read_b128 v[82:85], v1 offset:2048
	ds_read_b128 v[86:89], v1 offset:3072
	s_add_u32 s4, s48, 0x40000
	s_addc_u32 s5, s49, 0
	s_mov_b32 m0, s55
	v_lshl_add_u64 v[134:135], s[4:5], 0, v[164:165]
	ds_read_b128 v[118:121], v206 offset:32768
	ds_read_b128 v[130:133], v206 offset:33792
	ds_read_b128 v[170:173], v206 offset:34816
	ds_read_b128 v[174:177], v206 offset:35840
	ds_read_b128 v[178:181], v206 offset:36864
	ds_read_b128 v[182:185], v206 offset:37888
	ds_read_b128 v[186:189], v206 offset:38912
	ds_read_b128 v[208:211], v206 offset:39936
	global_load_lds_dwordx4 v[134:135], off
	v_lshl_add_u64 v[134:135], s[4:5], 0, v[162:163]
	s_mov_b32 m0, s56
	s_nop 0
	global_load_lds_dwordx4 v[134:135], off
	s_waitcnt lgkmcnt(8)
	s_barrier
	s_waitcnt lgkmcnt(0)
	s_waitcnt lgkmcnt(0)
	v_mfma_f32_16x16x32_bf16 v[134:137], v[54:57], v[118:121], v[158:161]
	v_mfma_f32_16x16x32_bf16 v[158:161], v[70:73], v[130:133], v[134:137]
	v_mfma_f32_16x16x32_bf16 v[134:137], v[82:85], v[118:121], v[154:157]
	v_mfma_f32_16x16x32_bf16 v[154:157], v[86:89], v[130:133], v[134:137]
	v_mfma_f32_16x16x32_bf16 v[134:137], v[54:57], v[170:173], v[142:145]
	v_mfma_f32_16x16x32_bf16 v[142:145], v[70:73], v[174:177], v[134:137]
	v_mfma_f32_16x16x32_bf16 v[134:137], v[82:85], v[170:173], v[138:141]
	v_mfma_f32_16x16x32_bf16 v[126:129], v[54:57], v[178:181], v[126:129]
	v_mfma_f32_16x16x32_bf16 v[122:125], v[82:85], v[178:181], v[122:125]
	v_mfma_f32_16x16x32_bf16 v[110:113], v[54:57], v[186:189], v[110:113]
	v_mfma_f32_16x16x32_bf16 v[106:109], v[82:85], v[186:189], v[106:109]
	v_mfma_f32_16x16x32_bf16 v[138:141], v[86:89], v[174:177], v[134:137]
	v_mfma_f32_16x16x32_bf16 v[126:129], v[70:73], v[182:185], v[126:129]
	v_mfma_f32_16x16x32_bf16 v[122:125], v[86:89], v[182:185], v[122:125]
	v_mfma_f32_16x16x32_bf16 v[110:113], v[70:73], v[208:211], v[110:113]
	v_mfma_f32_16x16x32_bf16 v[106:109], v[86:89], v[208:211], v[106:109]
	s_barrier
	s_add_i32 s48, 0, 0x1c000
	s_add_i32 s4, s67, s52
	v_add_u32_e32 v1, s48, v191
	v_lshl_add_u64 v[134:135], v[214:215], 0, s[22:23]
	s_mov_b32 m0, s4
	ds_read_b128 v[222:225], v1
	ds_read_b128 v[226:229], v1 offset:1024
	ds_read_b128 v[230:233], v1 offset:2048
	ds_read_b128 v[234:237], v1 offset:3072
	global_load_lds_dwordx4 v[134:135], off
	v_lshl_add_u64 v[134:135], v[238:239], 0, s[22:23]
	s_add_i32 m0, s4, 0x2000
	s_nop 0
	global_load_lds_dwordx4 v[134:135], off
	s_barrier
	s_waitcnt lgkmcnt(0)
	s_waitcnt lgkmcnt(0)
	v_mfma_f32_16x16x32_bf16 v[50:53], v[230:233], v[118:121], v[50:53]
	v_mfma_f32_16x16x32_bf16 v[134:137], v[222:225], v[118:121], v[150:153]
	v_mfma_f32_16x16x32_bf16 v[146:149], v[234:237], v[130:133], v[50:53]
	v_mfma_f32_16x16x32_bf16 v[50:53], v[222:225], v[170:173], v[58:61]
	v_mfma_f32_16x16x32_bf16 v[150:153], v[226:229], v[130:133], v[134:137]
	v_mfma_f32_16x16x32_bf16 v[134:137], v[226:229], v[174:177], v[50:53]
	v_mfma_f32_16x16x32_bf16 v[50:53], v[230:233], v[170:173], v[62:65]
	v_mfma_f32_16x16x32_bf16 v[130:133], v[234:237], v[174:177], v[50:53]
	v_mfma_f32_16x16x32_bf16 v[50:53], v[222:225], v[178:181], v[66:69]
	v_mfma_f32_16x16x32_bf16 v[118:121], v[226:229], v[182:185], v[50:53]
	v_mfma_f32_16x16x32_bf16 v[50:53], v[230:233], v[178:181], v[114:117]
	v_mfma_f32_16x16x32_bf16 v[114:117], v[234:237], v[182:185], v[50:53]
	v_mfma_f32_16x16x32_bf16 v[50:53], v[222:225], v[186:189], v[102:105]
	v_mfma_f32_16x16x32_bf16 v[102:105], v[226:229], v[208:211], v[50:53]
	v_mfma_f32_16x16x32_bf16 v[50:53], v[230:233], v[186:189], v[98:101]
	v_mfma_f32_16x16x32_bf16 v[98:101], v[234:237], v[208:211], v[50:53]
	s_mov_b32 m0, s58
	v_lshl_add_u64 v[186:187], v[240:241], 0, s[22:23]
	s_barrier
	s_nop 2
	ds_read_b128 v[50:53], v206 offset:49152
	ds_read_b128 v[58:61], v206 offset:50176
	ds_read_b128 v[62:65], v206 offset:51200
	ds_read_b128 v[66:69], v206 offset:52224
	ds_read_b128 v[170:173], v206 offset:53248
	ds_read_b128 v[174:177], v206 offset:54272
	ds_read_b128 v[178:181], v206 offset:55296
	ds_read_b128 v[182:185], v206 offset:56320
	global_load_lds_dwordx4 v[186:187], off
	v_lshl_add_u64 v[186:187], v[242:243], 0, s[22:23]
	s_mov_b32 m0, s59
	s_nop 0
	global_load_lds_dwordx4 v[186:187], off
	s_barrier
	s_waitcnt lgkmcnt(0)
	s_waitcnt lgkmcnt(0)
	v_mfma_f32_16x16x32_bf16 v[94:97], v[54:57], v[50:53], v[94:97]
	v_mfma_f32_16x16x32_bf16 v[90:93], v[82:85], v[50:53], v[90:93]
	v_mfma_f32_16x16x32_bf16 v[78:81], v[54:57], v[62:65], v[78:81]
	v_mfma_f32_16x16x32_bf16 v[74:77], v[82:85], v[62:65], v[74:77]
	v_mfma_f32_16x16x32_bf16 v[30:33], v[54:57], v[170:173], v[30:33]
	v_mfma_f32_16x16x32_bf16 v[26:29], v[82:85], v[170:173], v[26:29]
	v_mfma_f32_16x16x32_bf16 v[14:17], v[54:57], v[178:181], v[14:17]
	v_mfma_f32_16x16x32_bf16 v[10:13], v[82:85], v[178:181], v[10:13]
	v_mfma_f32_16x16x32_bf16 v[94:97], v[70:73], v[58:61], v[94:97]
	v_mfma_f32_16x16x32_bf16 v[90:93], v[86:89], v[58:61], v[90:93]
	v_mfma_f32_16x16x32_bf16 v[78:81], v[70:73], v[66:69], v[78:81]
	v_mfma_f32_16x16x32_bf16 v[74:77], v[86:89], v[66:69], v[74:77]
	v_mfma_f32_16x16x32_bf16 v[30:33], v[70:73], v[174:177], v[30:33]
	v_mfma_f32_16x16x32_bf16 v[26:29], v[86:89], v[174:177], v[26:29]
	v_mfma_f32_16x16x32_bf16 v[14:17], v[70:73], v[182:185], v[14:17]
	v_mfma_f32_16x16x32_bf16 v[10:13], v[86:89], v[182:185], v[10:13]
	s_barrier
	s_add_u32 s4, s46, 0x40080
	s_addc_u32 s5, s47, 0
	s_add_i32 s46, s48, s52
	v_lshl_add_u64 v[54:55], s[4:5], 0, v[164:165]
	s_mov_b32 m0, s46
	s_nop 0
	global_load_lds_dwordx4 v[54:55], off
	v_lshl_add_u64 v[54:55], s[4:5], 0, v[162:163]
	s_add_i32 m0, s46, 0x2000
	s_nop 0
	global_load_lds_dwordx4 v[54:55], off
	s_waitcnt vmcnt(6)
	s_barrier
	v_mfma_f32_16x16x32_bf16 v[34:37], v[222:225], v[50:53], v[34:37]
	v_mfma_f32_16x16x32_bf16 v[86:89], v[226:229], v[58:61], v[34:37]
	v_mfma_f32_16x16x32_bf16 v[34:37], v[230:233], v[50:53], v[38:41]
	v_mfma_f32_16x16x32_bf16 v[82:85], v[234:237], v[58:61], v[34:37]
	v_mfma_f32_16x16x32_bf16 v[34:37], v[222:225], v[62:65], v[42:45]
	v_mfma_f32_16x16x32_bf16 v[70:73], v[226:229], v[66:69], v[34:37]
	v_mfma_f32_16x16x32_bf16 v[34:37], v[230:233], v[62:65], v[46:49]
	v_mfma_f32_16x16x32_bf16 v[22:25], v[222:225], v[170:173], v[22:25]
	v_mfma_f32_16x16x32_bf16 v[18:21], v[230:233], v[170:173], v[18:21]
	v_mfma_f32_16x16x32_bf16 v[6:9], v[222:225], v[178:181], v[6:9]
	v_mfma_f32_16x16x32_bf16 v[2:5], v[230:233], v[178:181], v[2:5]
	v_mfma_f32_16x16x32_bf16 v[54:57], v[234:237], v[66:69], v[34:37]
	v_mfma_f32_16x16x32_bf16 v[22:25], v[226:229], v[174:177], v[22:25]
	v_mfma_f32_16x16x32_bf16 v[18:21], v[234:237], v[174:177], v[18:21]
	v_mfma_f32_16x16x32_bf16 v[6:9], v[226:229], v[182:185], v[6:9]
	v_mfma_f32_16x16x32_bf16 v[2:5], v[234:237], v[182:185], v[2:5]
	s_add_i32 s66, s66, 2
	s_add_u32 s64, s64, 0x100
	s_addc_u32 s65, s65, 0
	s_cmp_gt_u32 s66, 13
	s_mov_b64 s[4:5], s[36:37]
	s_barrier
	s_nop 0
